# LayerNorm wave_sum xor16/xor32 steps via v_permlane16/32_swap (no LDS shuffles left in LayerNorm); plus pipelined x conversion
# baseline (speedup 1.0000x reference)
; __device__ __forceinline__ float wave_sum(float v) {
; #pragma unroll
;     for (int o = 1; o < 64; o <<= 1) v += __shfl_xor(v, o);
;     return v;
; __device__ __forceinline__ void ln_pass(h16* Y16, const float* g, const float* b) {
;     ...
;     for (int row0 = (blockIdx.x * 8 + wave) * 4; row0 < NTOK; row0 += gridDim.x * 32) {
;         h16x8 w[4][2];
; #pragma unroll
;         for (int r = 0; r < 4; ++r)
; #pragma unroll
;             for (int j = 0; j < 2; ++j) w[r][j] = *(const h16x8*)(Y16 + (size_t)(row0 + r) * DM + 8 * lane + 512 * j);
; #pragma unroll
;         for (int r = 0; r < 4; ++r) {
;             h16* yr = Y16 + (size_t)(row0 + r) * DM + 8 * lane; f32x4 v[4]; float s = 0.f;
; #pragma unroll
;             for (int j = 0; j < 2; ++j) {
;                 v[2 * j] = (f32x4){(float)w[r][j][0], (float)w[r][j][1], (float)w[r][j][2], (float)w[r][j][3]}; v[2 * j + 1] = (f32x4){(float)w[r][j][4], (float)w[r][j][5], (float)w[r][j][6], (float)w[r][j][7]}; }
; #pragma unroll
;             for (int j = 0; j < 4; ++j) s += (v[j].x + v[j].y) + (v[j].z + v[j].w);
;             const float mean = wave_sum(s) * (1.f / DM); float s2 = 0.f;
; #pragma unroll
;             for (int j = 0; j < 4; ++j) { v[j] = v[j] - mean; s2 += (v[j].x * v[j].x + v[j].y * v[j].y) + (v[j].z * v[j].z + v[j].w * v[j].w); }
;             const float rstd = 1.f / sqrtf(wave_sum(s2) * (1.f / DM) + LN_EPS);
.LBB0_1063:
	v_ashrrev_i32_e32 v57, 31, v56
	v_lshlrev_b64 v[32:33], 11, v[56:57]
	v_lshl_add_u64 v[70:71], v[58:59], 0, v[32:33]
	global_load_dwordx4 v[66:69], v[70:71], off
	global_load_dwordx4 v[78:81], v[70:71], off offset:1024
	v_add_u32_e32 v32, 1, v56
	v_ashrrev_i32_e32 v33, 31, v32
	v_lshlrev_b64 v[32:33], 11, v[32:33]
	v_lshl_add_u64 v[64:65], v[58:59], 0, v[32:33]
	global_load_dwordx4 v[52:55], v[64:65], off
	global_load_dwordx4 v[48:51], v[64:65], off offset:1024
	v_add_u32_e32 v32, 2, v56
	v_ashrrev_i32_e32 v33, 31, v32
	v_lshlrev_b64 v[32:33], 11, v[32:33]
	v_lshl_add_u64 v[62:63], v[58:59], 0, v[32:33]
	v_add_u32_e32 v32, 3, v56
	v_ashrrev_i32_e32 v33, 31, v32
	v_lshlrev_b64 v[32:33], 11, v[32:33]
	v_lshl_add_u64 v[60:61], v[58:59], 0, v[32:33]
	global_load_dwordx4 v[44:47], v[62:63], off
	global_load_dwordx4 v[40:43], v[62:63], off offset:1024
	global_load_dwordx4 v[36:39], v[60:61], off
	global_load_dwordx4 v[32:35], v[60:61], off offset:1024
	v_add_u32_e32 v56, s69, v56
	s_waitcnt vmcnt(7)
	v_cvt_f32_f16_e32 v82, v66
	v_cvt_f32_f16_sdwa v84, v66 dst_sel:DWORD dst_unused:UNUSED_PAD src0_sel:WORD_1
	v_cvt_f32_f16_e32 v83, v67
	v_cvt_f32_f16_sdwa v85, v67 dst_sel:DWORD dst_unused:UNUSED_PAD src0_sel:WORD_1
	v_cvt_f32_f16_e32 v86, v68
	v_cvt_f32_f16_sdwa v88, v68 dst_sel:DWORD dst_unused:UNUSED_PAD src0_sel:WORD_1
	v_cvt_f32_f16_e32 v87, v69
	v_cvt_f32_f16_sdwa v89, v69 dst_sel:DWORD dst_unused:UNUSED_PAD src0_sel:WORD_1
	s_waitcnt vmcnt(6)
	v_cvt_f32_f16_e32 v57, v78
	v_cvt_f32_f16_sdwa v91, v78 dst_sel:DWORD dst_unused:UNUSED_PAD src0_sel:WORD_1
	v_cvt_f32_f16_e32 v93, v79
	v_cvt_f32_f16_sdwa v97, v79 dst_sel:DWORD dst_unused:UNUSED_PAD src0_sel:WORD_1
	v_pk_add_f32 v[82:83], v[82:83], v[84:85]
	v_cvt_f32_f16_e32 v90, v80
	v_cvt_f32_f16_sdwa v92, v80 dst_sel:DWORD dst_unused:UNUSED_PAD src0_sel:WORD_1
	v_cvt_f32_f16_sdwa v94, v81 dst_sel:DWORD dst_unused:UNUSED_PAD src0_sel:WORD_1
	v_cvt_f32_f16_e32 v96, v81
	v_add_f32_e32 v82, v82, v83
	v_add_f32_e32 v95, 0, v82
	v_pk_add_f32 v[82:83], v[86:87], v[88:89]
	v_add_f32_e32 v91, v57, v91
	v_pk_add_f32 v[82:83], v[82:83], v[82:83] op_sel_hi:[0,1]
	v_add_f32_e32 v93, v93, v97
	v_mov_b32_e32 v97, v83
	v_pk_add_f32 v[84:85], v[90:91], v[92:93]
	v_pk_add_f32 v[82:83], v[96:97], v[94:95]
	s_nop 0
	v_pk_add_f32 v[82:83], v[84:85], v[82:83]
	s_nop 0
	v_add_f32_e32 v57, v82, v83
	s_nop 1
	v_mov_b32_dpp v82, v57 quad_perm:[1,0,3,2] row_mask:0xf bank_mask:0xf
	s_waitcnt lgkmcnt(0)
	v_add_f32_e32 v57, v57, v82
	s_nop 1
	v_mov_b32_dpp v82, v57 quad_perm:[2,3,0,1] row_mask:0xf bank_mask:0xf
	s_waitcnt lgkmcnt(0)
	v_add_f32_e32 v57, v57, v82
	s_nop 1
	v_mov_b32_dpp v82, v57 row_ror:4 row_mask:0xf bank_mask:0xf
	s_waitcnt lgkmcnt(0)
	v_add_f32_e32 v57, v57, v82
	s_nop 1
	v_mov_b32_dpp v82, v57 row_ror:8 row_mask:0xf bank_mask:0xf
	s_waitcnt lgkmcnt(0)
	v_add_f32_e32 v57, v57, v82
	v_mov_b32_e32 v82, v57
	v_mov_b32_e32 v100, v57
	s_nop 1
	v_permlane16_swap_b32_e32 v82, v100
	v_add_f32_e32 v57, v82, v100
	v_mov_b32_e32 v82, v57
	v_mov_b32_e32 v100, v57
	s_nop 1
	v_permlane32_swap_b32_e32 v82, v100
	v_add_f32_e32 v57, v82, v100
	v_fma_mix_f32 v83, v57, s73, v66 op_sel:[0,0,1] op_sel_hi:[0,0,1]
	v_fma_mix_f32 v82, v57, s73, v66 op_sel_hi:[0,0,1]
	v_fma_mix_f32 v85, v57, s73, v67 op_sel:[0,0,1] op_sel_hi:[0,0,1]
	v_fma_mix_f32 v84, v57, s73, v67 op_sel_hi:[0,0,1]
	v_pk_mul_f32 v[66:67], v[84:85], v[84:85]
	v_pk_mul_f32 v[86:87], v[82:83], v[82:83]
	v_fma_mix_f32 v97, v57, s73, v81 op_sel:[0,0,1] op_sel_hi:[0,0,1]
	v_pk_mov_b32 v[88:89], v[86:87], v[66:67] op_sel:[1,0]
	v_mov_b32_e32 v87, v67
	v_pk_add_f32 v[66:67], v[88:89], v[86:87]
	v_fma_mix_f32 v87, v57, s73, v68 op_sel:[0,0,1] op_sel_hi:[0,0,1]
	v_fma_mix_f32 v86, v57, s73, v68 op_sel_hi:[0,0,1]
	v_fma_mix_f32 v89, v57, s73, v69 op_sel:[0,0,1] op_sel_hi:[0,0,1]
	v_fma_mix_f32 v88, v57, s73, v69 op_sel_hi:[0,0,1]
	v_pk_mul_f32 v[68:69], v[88:89], v[88:89]
	v_pk_mul_f32 v[90:91], v[86:87], v[86:87]
	v_pk_add_f32 v[66:67], v[66:67], v[66:67] op_sel_hi:[0,1]
	v_pk_mov_b32 v[92:93], v[90:91], v[68:69] op_sel:[1,0]
	v_mov_b32_e32 v91, v69
	v_pk_add_f32 v[68:69], v[92:93], v[90:91]
	v_fma_mix_f32 v90, v57, s73, v78 op_sel_hi:[0,0,1]
	v_fma_mix_f32 v91, v57, s73, v78 op_sel:[0,0,1] op_sel_hi:[0,0,1]
	v_fma_mix_f32 v92, v57, s73, v79 op_sel_hi:[0,0,1]
	v_mul_f32_e32 v66, v90, v90
	v_fma_mix_f32 v93, v57, s73, v79 op_sel:[0,0,1] op_sel_hi:[0,0,1]
	v_pk_fma_f32 v[78:79], v[90:91], v[90:91], v[66:67] op_sel_hi:[1,1,0]
	v_mul_f32_e32 v66, v92, v92
	v_pk_add_f32 v[68:69], v[68:69], v[68:69] op_sel_hi:[0,1]
	v_pk_fma_f32 v[94:95], v[92:93], v[92:93], v[66:67] op_sel_hi:[1,1,0]
	v_fma_mix_f32 v96, v57, s73, v81 op_sel_hi:[0,0,1]
	v_fma_mix_f32 v81, v57, s73, v80 op_sel:[0,0,1] op_sel_hi:[0,0,1]
	v_fma_mix_f32 v80, v57, s73, v80 op_sel_hi:[0,0,1]
	v_mul_f32_e32 v78, v80, v80
	v_mul_f32_e32 v94, v81, v81
	v_mul_f32_e32 v66, v96, v96
	v_mul_f32_e32 v68, v97, v97
	v_pk_add_f32 v[78:79], v[78:79], v[94:95]
	v_pk_add_f32 v[66:67], v[66:67], v[68:69]
	s_nop 0
	v_pk_add_f32 v[66:67], v[78:79], v[66:67]
	s_nop 0
	v_add_f32_e32 v57, v66, v67
	s_nop 1
	v_mov_b32_dpp v66, v57 quad_perm:[1,0,3,2] row_mask:0xf bank_mask:0xf
	s_waitcnt lgkmcnt(0)
	v_add_f32_e32 v57, v57, v66
	s_nop 1
	v_mov_b32_dpp v66, v57 quad_perm:[2,3,0,1] row_mask:0xf bank_mask:0xf
	s_waitcnt lgkmcnt(0)
	v_add_f32_e32 v57, v57, v66
	s_nop 1
	v_mov_b32_dpp v66, v57 row_ror:4 row_mask:0xf bank_mask:0xf
	s_waitcnt lgkmcnt(0)
	v_add_f32_e32 v57, v57, v66
	s_nop 1
	v_mov_b32_dpp v66, v57 row_ror:8 row_mask:0xf bank_mask:0xf
	s_waitcnt lgkmcnt(0)
; __device__ __forceinline__ float wave_sum(float v) {
; #pragma unroll
;     for (int o = 1; o < 64; o <<= 1) v += __shfl_xor(v, o);
;     return v;
; __device__ __forceinline__ void ln_pass(h16* Y16, const float* g, const float* b) {
;     ...
;             const float mean = wave_sum(s) * (1.f / DM); float s2 = 0.f;
; #pragma unroll
;             for (int j = 0; j < 4; ++j) { v[j] = v[j] - mean; s2 += (v[j].x * v[j].x + v[j].y * v[j].y) + (v[j].z * v[j].z + v[j].w * v[j].w); }
;             const float rstd = 1.f / sqrtf(wave_sum(s2) * (1.f / DM) + LN_EPS);
; #pragma unroll
;             for (int j = 0; j < 2; ++j) { const f32x4 o0 = v[2 * j] * rstd * gv[2 * j] + bv[2 * j], o1 = v[2 * j + 1] * rstd * gv[2 * j + 1] + bv[2 * j + 1]; h16x8 o;
;                 o[0] = (h16)o0.x; o[1] = (h16)o0.y; o[2] = (h16)o0.z; o[3] = (h16)o0.w; o[4] = (h16)o1.x; o[5] = (h16)o1.y; o[6] = (h16)o1.z; o[7] = (h16)o1.w;
;                 *(h16x8*)(yr + 512 * j) = o; }
	v_add_f32_e32 v57, v57, v66
	v_mov_b32_e32 v66, v57
	v_mov_b32_e32 v100, v57
	s_nop 1
	v_permlane16_swap_b32_e32 v66, v100
	v_add_f32_e32 v57, v66, v100
	v_mov_b32_e32 v66, v57
	v_mov_b32_e32 v100, v57
	s_nop 1
	v_permlane32_swap_b32_e32 v66, v100
	v_add_f32_e32 v57, v66, v100
	v_fmamk_f32 v57, v57, 0x3a800000, v213
	v_cmp_gt_f32_e32 vcc, s52, v57
	v_mul_f32_e32 v66, 0x4f800000, v57
	s_nop 0
	v_cndmask_b32_e32 v57, v57, v66, vcc
	v_sqrt_f32_e32 v66, v57
	s_nop 0
	v_add_u32_e32 v67, -1, v66
	v_fma_f32 v68, -v67, v66, v57
	v_cmp_ge_f32_e64 s[10:11], 0, v68
	v_add_u32_e32 v68, 1, v66
	s_nop 0
	v_cndmask_b32_e64 v67, v66, v67, s[10:11]
	v_fma_f32 v66, -v68, v66, v57
	v_cmp_lt_f32_e64 s[10:11], 0, v66
	s_nop 1
	v_cndmask_b32_e64 v66, v67, v68, s[10:11]
	v_mul_f32_e32 v67, 0x37800000, v66
	v_cndmask_b32_e32 v66, v66, v67, vcc
	v_cmp_class_f32_e32 vcc, v57, v214
	s_nop 1
	v_cndmask_b32_e32 v57, v66, v57, vcc
	v_div_scale_f32 v66, s[10:11], v57, v57, 1.0
	v_rcp_f32_e32 v67, v66
	s_nop 0
	v_fma_f32 v68, -v66, v67, 1.0
	v_fmac_f32_e32 v67, v68, v67
	v_div_scale_f32 v68, vcc, 1.0, v57, 1.0
	v_mul_f32_e32 v69, v68, v67
	v_fma_f32 v78, -v66, v69, v68
	v_fmac_f32_e32 v69, v78, v67
	v_fma_f32 v66, -v66, v69, v68
	v_div_fmas_f32 v66, v66, v67, v69
	v_div_fixup_f32 v78, v66, v57, 1.0
	v_pk_mul_f32 v[66:67], v[82:83], v[78:79] op_sel_hi:[1,0]
	v_pk_mul_f32 v[68:69], v[84:85], v[78:79] op_sel_hi:[1,0]
	v_pk_fma_f32 v[84:85], v[4:5], v[66:67], v[12:13]
	v_pk_fma_f32 v[82:83], v[6:7], v[68:69], v[14:15]
	v_pk_mul_f32 v[66:67], v[86:87], v[78:79] op_sel_hi:[1,0]
	v_pk_mul_f32 v[68:69], v[88:89], v[78:79] op_sel_hi:[1,0]
	v_pk_fma_f32 v[66:67], v[0:1], v[66:67], v[8:9]
	v_pk_fma_f32 v[68:69], v[2:3], v[68:69], v[10:11]
	s_waitcnt vmcnt(4)
	v_cvt_f32_f16_e32 v57, v48
	v_cvt_pk_f16_f32 v69, v68, v69
	v_cvt_pk_f16_f32 v68, v66, v67
	v_cvt_pk_f16_f32 v67, v82, v83
	v_cvt_pk_f16_f32 v66, v84, v85
	global_store_dwordx4 v[70:71], v[66:69], off
	v_cvt_f32_f16_sdwa v87, v49 dst_sel:DWORD dst_unused:UNUSED_PAD src0_sel:WORD_1
	v_cvt_f32_f16_e32 v86, v51
	v_pk_mul_f32 v[66:67], v[90:91], v[78:79] op_sel_hi:[1,0]
	v_pk_mul_f32 v[68:69], v[92:93], v[78:79] op_sel_hi:[1,0]
	v_pk_fma_f32 v[84:85], v[20:21], v[66:67], v[28:29]
	v_pk_fma_f32 v[82:83], v[22:23], v[68:69], v[30:31]
	v_pk_mul_f32 v[66:67], v[80:81], v[78:79] op_sel_hi:[1,0]
	v_pk_mul_f32 v[68:69], v[96:97], v[78:79] op_sel_hi:[1,0]
	v_pk_fma_f32 v[66:67], v[16:17], v[66:67], v[24:25]
	v_pk_fma_f32 v[68:69], v[18:19], v[68:69], v[26:27]
	v_cvt_f32_f16_sdwa v78, v54 dst_sel:DWORD dst_unused:UNUSED_PAD src0_sel:WORD_1
	v_cvt_pk_f16_f32 v69, v68, v69
	v_cvt_pk_f16_f32 v68, v66, v67
	v_cvt_pk_f16_f32 v67, v82, v83
	v_cvt_pk_f16_f32 v66, v84, v85
	global_store_dwordx4 v[70:71], v[66:69], off offset:1024
	v_cvt_f32_f16_e32 v70, v54
	v_cvt_f32_f16_e32 v71, v55
	v_cvt_f32_f16_e32 v66, v52
	v_cvt_f32_f16_sdwa v68, v52 dst_sel:DWORD dst_unused:UNUSED_PAD src0_sel:WORD_1
	v_cvt_f32_f16_e32 v67, v53
	v_cvt_f32_f16_sdwa v69, v53 dst_sel:DWORD dst_unused:UNUSED_PAD src0_sel:WORD_1
	v_cvt_f32_f16_sdwa v79, v55 dst_sel:DWORD dst_unused:UNUSED_PAD src0_sel:WORD_1
	v_cvt_f32_f16_sdwa v81, v48 dst_sel:DWORD dst_unused:UNUSED_PAD src0_sel:WORD_1
	v_cvt_f32_f16_e32 v83, v49
	v_pk_add_f32 v[66:67], v[66:67], v[68:69]
	v_cvt_f32_f16_e32 v80, v50
	v_cvt_f32_f16_sdwa v82, v50 dst_sel:DWORD dst_unused:UNUSED_PAD src0_sel:WORD_1
	v_cvt_f32_f16_sdwa v84, v51 dst_sel:DWORD dst_unused:UNUSED_PAD src0_sel:WORD_1
	v_add_f32_e32 v66, v66, v67
	v_add_f32_e32 v85, 0, v66
	v_pk_add_f32 v[66:67], v[70:71], v[78:79]
	v_add_f32_e32 v81, v57, v81
	v_pk_add_f32 v[66:67], v[66:67], v[66:67] op_sel_hi:[0,1]
	v_add_f32_e32 v83, v83, v87
	v_mov_b32_e32 v87, v67
	v_pk_add_f32 v[68:69], v[80:81], v[82:83]
	v_pk_add_f32 v[66:67], v[86:87], v[84:85]
	s_nop 0
	v_pk_add_f32 v[66:67], v[68:69], v[66:67]
	s_nop 0
	v_add_f32_e32 v57, v66, v67
	s_nop 1
	v_mov_b32_dpp v66, v57 quad_perm:[1,0,3,2] row_mask:0xf bank_mask:0xf
	s_waitcnt lgkmcnt(0)
	v_add_f32_e32 v57, v57, v66
	s_nop 1
	v_mov_b32_dpp v66, v57 quad_perm:[2,3,0,1] row_mask:0xf bank_mask:0xf
	s_waitcnt lgkmcnt(0)
	v_add_f32_e32 v57, v57, v66
	s_nop 1
	v_mov_b32_dpp v66, v57 row_ror:4 row_mask:0xf bank_mask:0xf
	s_waitcnt lgkmcnt(0)
	v_add_f32_e32 v57, v57, v66
	s_nop 1
	v_mov_b32_dpp v66, v57 row_ror:8 row_mask:0xf bank_mask:0xf
	s_waitcnt lgkmcnt(0)
	v_add_f32_e32 v57, v57, v66
	v_mov_b32_e32 v66, v57
	v_mov_b32_e32 v100, v57
	s_nop 1
	v_permlane16_swap_b32_e32 v66, v100
	v_add_f32_e32 v57, v66, v100
	v_mov_b32_e32 v66, v57
	v_mov_b32_e32 v100, v57
	s_nop 1
	v_permlane32_swap_b32_e32 v66, v100
	v_add_f32_e32 v57, v66, v100
	v_fma_mix_f32 v67, v57, s73, v52 op_sel:[0,0,1] op_sel_hi:[0,0,1]
	v_fma_mix_f32 v66, v57, s73, v52 op_sel_hi:[0,0,1]
	v_fma_mix_f32 v69, v57, s73, v53 op_sel:[0,0,1] op_sel_hi:[0,0,1]
	v_fma_mix_f32 v68, v57, s73, v53 op_sel_hi:[0,0,1]
	v_pk_mul_f32 v[52:53], v[68:69], v[68:69]
	v_pk_mul_f32 v[70:71], v[66:67], v[66:67]
	v_fma_mix_f32 v87, v57, s73, v51 op_sel:[0,0,1] op_sel_hi:[0,0,1]
	v_pk_mov_b32 v[78:79], v[70:71], v[52:53] op_sel:[1,0]
	v_mov_b32_e32 v71, v53
	v_pk_add_f32 v[52:53], v[78:79], v[70:71]
	v_fma_mix_f32 v71, v57, s73, v55 op_sel:[0,0,1] op_sel_hi:[0,0,1]
	v_pk_add_f32 v[78:79], v[52:53], v[52:53] op_sel_hi:[0,1]
	v_fma_mix_f32 v53, v57, s73, v54 op_sel:[0,0,1] op_sel_hi:[0,0,1]
	v_fma_mix_f32 v52, v57, s73, v54 op_sel_hi:[0,0,1]
	v_fma_mix_f32 v70, v57, s73, v55 op_sel_hi:[0,0,1]
	v_pk_mul_f32 v[54:55], v[70:71], v[70:71]
	v_pk_mul_f32 v[80:81], v[52:53], v[52:53]
	v_fma_mix_f32 v86, v57, s73, v51 op_sel_hi:[0,0,1]
	v_pk_mov_b32 v[82:83], v[80:81], v[54:55] op_sel:[1,0]
	v_mov_b32_e32 v81, v55
	v_pk_add_f32 v[54:55], v[82:83], v[80:81]
	v_fma_mix_f32 v80, v57, s73, v48 op_sel_hi:[0,0,1]
	v_fma_mix_f32 v81, v57, s73, v48 op_sel:[0,0,1] op_sel_hi:[0,0,1]
	v_mul_f32_e32 v48, v80, v80
	v_fma_mix_f32 v83, v57, s73, v49 op_sel:[0,0,1] op_sel_hi:[0,0,1]
	v_fma_mix_f32 v82, v57, s73, v49 op_sel_hi:[0,0,1]
	v_pk_fma_f32 v[48:49], v[80:81], v[80:81], v[48:49] op_sel_hi:[1,1,0]
	v_pk_add_f32 v[54:55], v[54:55], v[54:55] op_sel_hi:[0,1]
	v_mul_f32_e32 v48, v82, v82
	v_pk_fma_f32 v[84:85], v[82:83], v[82:83], v[48:49] op_sel_hi:[1,1,0]
	v_fma_mix_f32 v89, v57, s73, v50 op_sel:[0,0,1] op_sel_hi:[0,0,1]
	v_fma_mix_f32 v88, v57, s73, v50 op_sel_hi:[0,0,1]
	v_mul_f32_e32 v48, v88, v88
	v_mul_f32_e32 v84, v89, v89
	v_mul_f32_e32 v78, v86, v86
	v_mul_f32_e32 v54, v87, v87
	v_pk_add_f32 v[48:49], v[48:49], v[84:85]
	v_pk_add_f32 v[50:51], v[78:79], v[54:55]
	s_waitcnt vmcnt(4)
; __device__ __forceinline__ float wave_sum(float v) {
; #pragma unroll
;     for (int o = 1; o < 64; o <<= 1) v += __shfl_xor(v, o);
;     return v;
; __device__ __forceinline__ void ln_pass(h16* Y16, const float* g, const float* b) {
;     ...
;             const float mean = wave_sum(s) * (1.f / DM); float s2 = 0.f;
; #pragma unroll
;             for (int j = 0; j < 4; ++j) { v[j] = v[j] - mean; s2 += (v[j].x * v[j].x + v[j].y * v[j].y) + (v[j].z * v[j].z + v[j].w * v[j].w); }
;             const float rstd = 1.f / sqrtf(wave_sum(s2) * (1.f / DM) + LN_EPS);
; #pragma unroll
;             for (int j = 0; j < 2; ++j) { const f32x4 o0 = v[2 * j] * rstd * gv[2 * j] + bv[2 * j], o1 = v[2 * j + 1] * rstd * gv[2 * j + 1] + bv[2 * j + 1]; h16x8 o;
;                 o[0] = (h16)o0.x; o[1] = (h16)o0.y; o[2] = (h16)o0.z; o[3] = (h16)o0.w; o[4] = (h16)o1.x; o[5] = (h16)o1.y; o[6] = (h16)o1.z; o[7] = (h16)o1.w;
;                 *(h16x8*)(yr + 512 * j) = o; }
	v_cvt_f32_f16_e32 v57, v40
	v_pk_add_f32 v[48:49], v[48:49], v[50:51]
	s_nop 0
	v_add_f32_e32 v48, v48, v49
	s_nop 1
	v_mov_b32_dpp v49, v48 quad_perm:[1,0,3,2] row_mask:0xf bank_mask:0xf
	s_waitcnt lgkmcnt(0)
	v_add_f32_e32 v48, v48, v49
	s_nop 1
	v_mov_b32_dpp v49, v48 quad_perm:[2,3,0,1] row_mask:0xf bank_mask:0xf
	s_waitcnt lgkmcnt(0)
	v_add_f32_e32 v48, v48, v49
	s_nop 1
	v_mov_b32_dpp v49, v48 row_ror:4 row_mask:0xf bank_mask:0xf
	s_waitcnt lgkmcnt(0)
	v_add_f32_e32 v48, v48, v49
	s_nop 1
	v_mov_b32_dpp v49, v48 row_ror:8 row_mask:0xf bank_mask:0xf
	s_waitcnt lgkmcnt(0)
	v_add_f32_e32 v48, v48, v49
	v_mov_b32_e32 v49, v48
	v_mov_b32_e32 v100, v48
	s_nop 1
	v_permlane16_swap_b32_e32 v49, v100
	v_add_f32_e32 v48, v49, v100
	v_mov_b32_e32 v49, v48
	v_mov_b32_e32 v100, v48
	s_nop 1
	v_permlane32_swap_b32_e32 v49, v100
	v_add_f32_e32 v48, v49, v100
	v_fmamk_f32 v48, v48, 0x3a800000, v213
	v_cmp_gt_f32_e32 vcc, s52, v48
	v_mul_f32_e32 v49, 0x4f800000, v48
	s_nop 0
	v_cndmask_b32_e32 v48, v48, v49, vcc
	v_sqrt_f32_e32 v49, v48
	s_nop 0
	v_add_u32_e32 v50, -1, v49
	v_fma_f32 v51, -v50, v49, v48
	v_cmp_ge_f32_e64 s[10:11], 0, v51
	v_add_u32_e32 v51, 1, v49
	s_nop 0
	v_cndmask_b32_e64 v50, v49, v50, s[10:11]
	v_fma_f32 v49, -v51, v49, v48
	v_cmp_lt_f32_e64 s[10:11], 0, v49
	s_nop 1
	v_cndmask_b32_e64 v49, v50, v51, s[10:11]
	v_mul_f32_e32 v50, 0x37800000, v49
	v_cndmask_b32_e32 v49, v49, v50, vcc
	v_cmp_class_f32_e32 vcc, v48, v214
	s_nop 1
	v_cndmask_b32_e32 v48, v49, v48, vcc
	v_div_scale_f32 v49, s[10:11], v48, v48, 1.0
	v_rcp_f32_e32 v50, v49
	s_nop 0
	v_fma_f32 v51, -v49, v50, 1.0
	v_fmac_f32_e32 v50, v51, v50
	v_div_scale_f32 v51, vcc, 1.0, v48, 1.0
	v_mul_f32_e32 v54, v51, v50
	v_fma_f32 v55, -v49, v54, v51
	v_fmac_f32_e32 v54, v55, v50
	v_fma_f32 v49, -v49, v54, v51
	v_div_fmas_f32 v49, v49, v50, v54
	v_div_fixup_f32 v54, v49, v48, 1.0
	v_pk_mul_f32 v[48:49], v[66:67], v[54:55] op_sel_hi:[1,0]
	v_pk_mul_f32 v[50:51], v[68:69], v[54:55] op_sel_hi:[1,0]
	v_pk_fma_f32 v[68:69], v[4:5], v[48:49], v[12:13]
	v_pk_fma_f32 v[66:67], v[6:7], v[50:51], v[14:15]
	v_pk_mul_f32 v[48:49], v[52:53], v[54:55] op_sel_hi:[1,0]
	v_pk_mul_f32 v[50:51], v[70:71], v[54:55] op_sel_hi:[1,0]
	v_pk_fma_f32 v[48:49], v[0:1], v[48:49], v[8:9]
	v_pk_fma_f32 v[50:51], v[2:3], v[50:51], v[10:11]
	v_cvt_f32_f16_sdwa v71, v41 dst_sel:DWORD dst_unused:UNUSED_PAD src0_sel:WORD_1
	v_cvt_pk_f16_f32 v51, v50, v51
	v_cvt_pk_f16_f32 v50, v48, v49
	v_cvt_pk_f16_f32 v49, v66, v67
	v_cvt_pk_f16_f32 v48, v68, v69
	global_store_dwordx4 v[64:65], v[48:51], off
	v_cvt_f32_f16_sdwa v68, v43 dst_sel:DWORD dst_unused:UNUSED_PAD src0_sel:WORD_1
	v_cvt_f32_f16_e32 v70, v43
	v_pk_mul_f32 v[48:49], v[80:81], v[54:55] op_sel_hi:[1,0]
	v_pk_mul_f32 v[50:51], v[82:83], v[54:55] op_sel_hi:[1,0]
	v_pk_fma_f32 v[66:67], v[20:21], v[48:49], v[28:29]
	v_pk_fma_f32 v[52:53], v[22:23], v[50:51], v[30:31]
	v_pk_mul_f32 v[48:49], v[88:89], v[54:55] op_sel_hi:[1,0]
	v_pk_mul_f32 v[50:51], v[86:87], v[54:55] op_sel_hi:[1,0]
	v_pk_fma_f32 v[48:49], v[16:17], v[48:49], v[24:25]
	v_pk_fma_f32 v[50:51], v[18:19], v[50:51], v[26:27]
	v_cvt_f32_f16_sdwa v54, v46 dst_sel:DWORD dst_unused:UNUSED_PAD src0_sel:WORD_1
	v_cvt_pk_f16_f32 v51, v50, v51
	v_cvt_pk_f16_f32 v50, v48, v49
	v_cvt_pk_f16_f32 v49, v52, v53
	v_cvt_pk_f16_f32 v48, v66, v67
	global_store_dwordx4 v[64:65], v[48:51], off offset:1024
	v_cvt_f32_f16_e32 v52, v46
	v_cvt_f32_f16_e32 v53, v47
	v_cvt_f32_f16_e32 v48, v44
	v_cvt_f32_f16_sdwa v50, v44 dst_sel:DWORD dst_unused:UNUSED_PAD src0_sel:WORD_1
	v_cvt_f32_f16_e32 v49, v45
	v_cvt_f32_f16_sdwa v51, v45 dst_sel:DWORD dst_unused:UNUSED_PAD src0_sel:WORD_1
	v_cvt_f32_f16_sdwa v55, v47 dst_sel:DWORD dst_unused:UNUSED_PAD src0_sel:WORD_1
	v_cvt_f32_f16_sdwa v65, v40 dst_sel:DWORD dst_unused:UNUSED_PAD src0_sel:WORD_1
	v_cvt_f32_f16_e32 v67, v41
	v_pk_add_f32 v[48:49], v[48:49], v[50:51]
	v_cvt_f32_f16_e32 v64, v42
	v_cvt_f32_f16_sdwa v66, v42 dst_sel:DWORD dst_unused:UNUSED_PAD src0_sel:WORD_1
	v_add_f32_e32 v48, v48, v49
	v_add_f32_e32 v69, 0, v48
	v_pk_add_f32 v[48:49], v[52:53], v[54:55]
	v_add_f32_e32 v65, v57, v65
	v_pk_add_f32 v[48:49], v[48:49], v[48:49] op_sel_hi:[0,1]
	v_add_f32_e32 v67, v67, v71
	v_mov_b32_e32 v71, v49
	v_pk_add_f32 v[50:51], v[64:65], v[66:67]
	v_pk_add_f32 v[48:49], v[70:71], v[68:69]
	s_nop 0
	v_pk_add_f32 v[48:49], v[50:51], v[48:49]
	s_nop 0
	v_add_f32_e32 v48, v48, v49
	s_nop 1
	v_mov_b32_dpp v49, v48 quad_perm:[1,0,3,2] row_mask:0xf bank_mask:0xf
	s_waitcnt lgkmcnt(0)
	v_add_f32_e32 v48, v48, v49
	s_nop 1
	v_mov_b32_dpp v49, v48 quad_perm:[2,3,0,1] row_mask:0xf bank_mask:0xf
	s_waitcnt lgkmcnt(0)
	v_add_f32_e32 v48, v48, v49
	s_nop 1
	v_mov_b32_dpp v49, v48 row_ror:4 row_mask:0xf bank_mask:0xf
	s_waitcnt lgkmcnt(0)
	v_add_f32_e32 v48, v48, v49
	s_nop 1
	v_mov_b32_dpp v49, v48 row_ror:8 row_mask:0xf bank_mask:0xf
	s_waitcnt lgkmcnt(0)
; __device__ __forceinline__ float wave_sum(float v) {
; #pragma unroll
;     for (int o = 1; o < 64; o <<= 1) v += __shfl_xor(v, o);
;     return v;
; __device__ __forceinline__ void ln_pass(h16* Y16, const float* g, const float* b) {
;     ...
;             const float mean = wave_sum(s) * (1.f / DM); float s2 = 0.f;
; #pragma unroll
;             for (int j = 0; j < 4; ++j) { v[j] = v[j] - mean; s2 += (v[j].x * v[j].x + v[j].y * v[j].y) + (v[j].z * v[j].z + v[j].w * v[j].w); }
;             const float rstd = 1.f / sqrtf(wave_sum(s2) * (1.f / DM) + LN_EPS);
; #pragma unroll
;             for (int j = 0; j < 2; ++j) { const f32x4 o0 = v[2 * j] * rstd * gv[2 * j] + bv[2 * j], o1 = v[2 * j + 1] * rstd * gv[2 * j + 1] + bv[2 * j + 1]; h16x8 o;
;                 o[0] = (h16)o0.x; o[1] = (h16)o0.y; o[2] = (h16)o0.z; o[3] = (h16)o0.w; o[4] = (h16)o1.x; o[5] = (h16)o1.y; o[6] = (h16)o1.z; o[7] = (h16)o1.w;
;                 *(h16x8*)(yr + 512 * j) = o; }
	v_add_f32_e32 v48, v48, v49
	v_mov_b32_e32 v49, v48
	v_mov_b32_e32 v100, v48
	s_nop 1
	v_permlane16_swap_b32_e32 v49, v100
	v_add_f32_e32 v48, v49, v100
	v_mov_b32_e32 v49, v48
	v_mov_b32_e32 v100, v48
	s_nop 1
	v_permlane32_swap_b32_e32 v49, v100
	v_add_f32_e32 v57, v49, v100
	v_fma_mix_f32 v49, v57, s73, v44 op_sel:[0,0,1] op_sel_hi:[0,0,1]
	v_fma_mix_f32 v48, v57, s73, v44 op_sel_hi:[0,0,1]
	v_fma_mix_f32 v51, v57, s73, v45 op_sel:[0,0,1] op_sel_hi:[0,0,1]
	v_fma_mix_f32 v50, v57, s73, v45 op_sel_hi:[0,0,1]
	v_pk_mul_f32 v[44:45], v[50:51], v[50:51]
	v_pk_mul_f32 v[52:53], v[48:49], v[48:49]
	v_fma_mix_f32 v71, v57, s73, v43 op_sel:[0,0,1] op_sel_hi:[0,0,1]
	v_pk_mov_b32 v[54:55], v[52:53], v[44:45] op_sel:[1,0]
	v_mov_b32_e32 v53, v45
	v_pk_add_f32 v[44:45], v[54:55], v[52:53]
	v_fma_mix_f32 v53, v57, s73, v46 op_sel:[0,0,1] op_sel_hi:[0,0,1]
	v_fma_mix_f32 v52, v57, s73, v46 op_sel_hi:[0,0,1]
	v_fma_mix_f32 v55, v57, s73, v47 op_sel:[0,0,1] op_sel_hi:[0,0,1]
	v_fma_mix_f32 v54, v57, s73, v47 op_sel_hi:[0,0,1]
	v_pk_mul_f32 v[46:47], v[54:55], v[54:55]
	v_pk_mul_f32 v[64:65], v[52:53], v[52:53]
	v_pk_add_f32 v[44:45], v[44:45], v[44:45] op_sel_hi:[0,1]
	v_pk_mov_b32 v[66:67], v[64:65], v[46:47] op_sel:[1,0]
	v_mov_b32_e32 v65, v47
	v_pk_add_f32 v[46:47], v[66:67], v[64:65]
	v_fma_mix_f32 v64, v57, s73, v40 op_sel_hi:[0,0,1]
	v_fma_mix_f32 v65, v57, s73, v40 op_sel:[0,0,1] op_sel_hi:[0,0,1]
	v_mul_f32_e32 v40, v64, v64
	v_fma_mix_f32 v67, v57, s73, v41 op_sel:[0,0,1] op_sel_hi:[0,0,1]
	v_fma_mix_f32 v66, v57, s73, v41 op_sel_hi:[0,0,1]
	v_pk_fma_f32 v[40:41], v[64:65], v[64:65], v[40:41] op_sel_hi:[1,1,0]
	v_pk_add_f32 v[46:47], v[46:47], v[46:47] op_sel_hi:[0,1]
	v_mul_f32_e32 v40, v66, v66
	v_pk_fma_f32 v[68:69], v[66:67], v[66:67], v[40:41] op_sel_hi:[1,1,0]
	v_fma_mix_f32 v70, v57, s73, v43 op_sel_hi:[0,0,1]
	v_fma_mix_f32 v79, v57, s73, v42 op_sel:[0,0,1] op_sel_hi:[0,0,1]
	v_fma_mix_f32 v78, v57, s73, v42 op_sel_hi:[0,0,1]
	v_mul_f32_e32 v40, v78, v78
	v_mul_f32_e32 v68, v79, v79
	v_mul_f32_e32 v44, v70, v70
	v_mul_f32_e32 v46, v71, v71
	v_pk_add_f32 v[40:41], v[40:41], v[68:69]
	v_pk_add_f32 v[42:43], v[44:45], v[46:47]
	s_waitcnt vmcnt(4)
	v_cvt_f32_f16_sdwa v57, v33 dst_sel:DWORD dst_unused:UNUSED_PAD src0_sel:WORD_1
	v_pk_add_f32 v[40:41], v[40:41], v[42:43]
	s_nop 0
	v_add_f32_e32 v40, v40, v41
	s_nop 1
	v_mov_b32_dpp v41, v40 quad_perm:[1,0,3,2] row_mask:0xf bank_mask:0xf
	s_waitcnt lgkmcnt(0)
	v_add_f32_e32 v40, v40, v41
	s_nop 1
	v_mov_b32_dpp v41, v40 quad_perm:[2,3,0,1] row_mask:0xf bank_mask:0xf
	s_waitcnt lgkmcnt(0)
	v_add_f32_e32 v40, v40, v41
	s_nop 1
	v_mov_b32_dpp v41, v40 row_ror:4 row_mask:0xf bank_mask:0xf
	s_waitcnt lgkmcnt(0)
	v_add_f32_e32 v40, v40, v41
	s_nop 1
	v_mov_b32_dpp v41, v40 row_ror:8 row_mask:0xf bank_mask:0xf
	s_waitcnt lgkmcnt(0)
	v_add_f32_e32 v40, v40, v41
	v_mov_b32_e32 v41, v40
	v_mov_b32_e32 v100, v40
	s_nop 1
	v_permlane16_swap_b32_e32 v41, v100
	v_add_f32_e32 v40, v41, v100
	v_mov_b32_e32 v41, v40
	v_mov_b32_e32 v100, v40
	s_nop 1
	v_permlane32_swap_b32_e32 v41, v100
	v_add_f32_e32 v40, v41, v100
	v_fmamk_f32 v40, v40, 0x3a800000, v213
	v_cmp_gt_f32_e32 vcc, s52, v40
	v_mul_f32_e32 v41, 0x4f800000, v40
	s_nop 0
	v_cndmask_b32_e32 v40, v40, v41, vcc
	v_sqrt_f32_e32 v41, v40
	s_nop 0
	v_add_u32_e32 v42, -1, v41
	v_fma_f32 v43, -v42, v41, v40
	v_cmp_ge_f32_e64 s[10:11], 0, v43
	v_add_u32_e32 v43, 1, v41
	s_nop 0
	v_cndmask_b32_e64 v42, v41, v42, s[10:11]
	v_fma_f32 v41, -v43, v41, v40
	v_cmp_lt_f32_e64 s[10:11], 0, v41
	s_nop 1
	v_cndmask_b32_e64 v41, v42, v43, s[10:11]
	v_mul_f32_e32 v42, 0x37800000, v41
	v_cndmask_b32_e32 v41, v41, v42, vcc
	v_cmp_class_f32_e32 vcc, v40, v214
	s_nop 1
	v_cndmask_b32_e32 v40, v41, v40, vcc
	v_div_scale_f32 v41, s[10:11], v40, v40, 1.0
	v_rcp_f32_e32 v42, v41
	s_nop 0
	v_fma_f32 v43, -v41, v42, 1.0
	v_fmac_f32_e32 v42, v43, v42
	v_div_scale_f32 v43, vcc, 1.0, v40, 1.0
	v_mul_f32_e32 v44, v43, v42
	v_fma_f32 v45, -v41, v44, v43
	v_fmac_f32_e32 v44, v45, v42
	v_fma_f32 v41, -v41, v44, v43
	v_div_fmas_f32 v41, v41, v42, v44
	v_div_fixup_f32 v44, v41, v40, 1.0
	v_pk_mul_f32 v[40:41], v[48:49], v[44:45] op_sel_hi:[1,0]
	v_pk_mul_f32 v[42:43], v[50:51], v[44:45] op_sel_hi:[1,0]
	v_pk_fma_f32 v[48:49], v[4:5], v[40:41], v[12:13]
	v_pk_fma_f32 v[46:47], v[6:7], v[42:43], v[14:15]
	v_pk_mul_f32 v[40:41], v[52:53], v[44:45] op_sel_hi:[1,0]
	v_pk_mul_f32 v[42:43], v[54:55], v[44:45] op_sel_hi:[1,0]
	v_pk_fma_f32 v[40:41], v[0:1], v[40:41], v[8:9]
	v_pk_fma_f32 v[42:43], v[2:3], v[42:43], v[10:11]
	v_cvt_f32_f16_sdwa v51, v32 dst_sel:DWORD dst_unused:UNUSED_PAD src0_sel:WORD_1
	v_cvt_pk_f16_f32 v43, v42, v43
	v_cvt_pk_f16_f32 v42, v40, v41
	v_cvt_pk_f16_f32 v41, v46, v47
	v_cvt_pk_f16_f32 v40, v48, v49
	global_store_dwordx4 v[62:63], v[40:43], off
	v_cvt_f32_f16_e32 v55, v33
	v_cvt_f32_f16_sdwa v50, v34 dst_sel:DWORD dst_unused:UNUSED_PAD src0_sel:WORD_1
	v_pk_mul_f32 v[40:41], v[64:65], v[44:45] op_sel_hi:[1,0]
	v_pk_mul_f32 v[42:43], v[66:67], v[44:45] op_sel_hi:[1,0]
	v_pk_fma_f32 v[48:49], v[20:21], v[40:41], v[28:29]
	v_pk_fma_f32 v[46:47], v[22:23], v[42:43], v[30:31]
	v_pk_mul_f32 v[40:41], v[78:79], v[44:45] op_sel_hi:[1,0]
	v_pk_mul_f32 v[42:43], v[70:71], v[44:45] op_sel_hi:[1,0]
	v_pk_fma_f32 v[40:41], v[16:17], v[40:41], v[24:25]
	v_pk_fma_f32 v[42:43], v[18:19], v[42:43], v[26:27]
	v_cvt_f32_f16_e32 v44, v38
	v_cvt_pk_f16_f32 v43, v42, v43
	v_cvt_pk_f16_f32 v42, v40, v41
	v_cvt_pk_f16_f32 v41, v46, v47
	v_cvt_pk_f16_f32 v40, v48, v49
	global_store_dwordx4 v[62:63], v[40:43], off offset:1024
	v_cvt_f32_f16_sdwa v46, v38 dst_sel:DWORD dst_unused:UNUSED_PAD src0_sel:WORD_1
	v_cvt_f32_f16_e32 v45, v39
	v_cvt_f32_f16_e32 v40, v36
	v_cvt_f32_f16_sdwa v42, v36 dst_sel:DWORD dst_unused:UNUSED_PAD src0_sel:WORD_1
	v_cvt_f32_f16_e32 v41, v37
	v_cvt_f32_f16_sdwa v43, v37 dst_sel:DWORD dst_unused:UNUSED_PAD src0_sel:WORD_1
	v_cvt_f32_f16_sdwa v47, v39 dst_sel:DWORD dst_unused:UNUSED_PAD src0_sel:WORD_1
	v_cvt_f32_f16_e32 v49, v32
	v_cvt_f32_f16_e32 v48, v34
	v_pk_add_f32 v[40:41], v[40:41], v[42:43]
	v_cvt_f32_f16_sdwa v52, v35 dst_sel:DWORD dst_unused:UNUSED_PAD src0_sel:WORD_1
	v_cvt_f32_f16_e32 v54, v35
	v_add_f32_e32 v40, v40, v41
	v_add_f32_e32 v53, 0, v40
	v_pk_add_f32 v[40:41], v[44:45], v[46:47]
	v_add_f32_e32 v49, v49, v51
	v_pk_add_f32 v[40:41], v[40:41], v[40:41] op_sel_hi:[0,1]
	v_add_f32_e32 v51, v55, v57
	v_mov_b32_e32 v55, v41
	v_pk_add_f32 v[42:43], v[48:49], v[50:51]
	v_pk_add_f32 v[40:41], v[54:55], v[52:53]
	s_nop 0
	v_pk_add_f32 v[40:41], v[42:43], v[40:41]
	s_nop 0
	v_add_f32_e32 v40, v40, v41
	s_nop 1
	v_mov_b32_dpp v41, v40 quad_perm:[1,0,3,2] row_mask:0xf bank_mask:0xf
	s_waitcnt lgkmcnt(0)
; __device__ __forceinline__ void ln_pass(h16* Y16, const float* g, const float* b) {
;     ...
;     for (int row0 = (blockIdx.x * 8 + wave) * 4; row0 < NTOK; row0 += gridDim.x * 32) {
;     ...
;         for (int r = 0; r < 4; ++r) {
;             h16* yr = Y16 + (size_t)(row0 + r) * DM + 8 * lane; f32x4 v[4]; float s = 0.f;
; #pragma unroll
;             for (int j = 0; j < 2; ++j) {
;                 v[2 * j] = (f32x4){(float)w[r][j][0], (float)w[r][j][1], (float)w[r][j][2], (float)w[r][j][3]}; v[2 * j + 1] = (f32x4){(float)w[r][j][4], (float)w[r][j][5], (float)w[r][j][6], (float)w[r][j][7]}; }
; #pragma unroll
;             for (int j = 0; j < 4; ++j) s += (v[j].x + v[j].y) + (v[j].z + v[j].w);
;             const float mean = wave_sum(s) * (1.f / DM); float s2 = 0.f;
; #pragma unroll
;             for (int j = 0; j < 4; ++j) { v[j] = v[j] - mean; s2 += (v[j].x * v[j].x + v[j].y * v[j].y) + (v[j].z * v[j].z + v[j].w * v[j].w); }
;             const float rstd = 1.f / sqrtf(wave_sum(s2) * (1.f / DM) + LN_EPS);
; #pragma unroll
;             for (int j = 0; j < 2; ++j) { const f32x4 o0 = v[2 * j] * rstd * gv[2 * j] + bv[2 * j], o1 = v[2 * j + 1] * rstd * gv[2 * j + 1] + bv[2 * j + 1]; h16x8 o;
;                 o[0] = (h16)o0.x; o[1] = (h16)o0.y; o[2] = (h16)o0.z; o[3] = (h16)o0.w; o[4] = (h16)o1.x; o[5] = (h16)o1.y; o[6] = (h16)o1.z; o[7] = (h16)o1.w;
;                 *(h16x8*)(yr + 512 * j) = o; }
;         }
	v_add_f32_e32 v40, v40, v41
	s_nop 1
	v_mov_b32_dpp v41, v40 quad_perm:[2,3,0,1] row_mask:0xf bank_mask:0xf
	s_waitcnt lgkmcnt(0)
	v_add_f32_e32 v40, v40, v41
	s_nop 1
	v_mov_b32_dpp v41, v40 row_ror:4 row_mask:0xf bank_mask:0xf
	s_waitcnt lgkmcnt(0)
	v_add_f32_e32 v40, v40, v41
	s_nop 1
	v_mov_b32_dpp v41, v40 row_ror:8 row_mask:0xf bank_mask:0xf
	s_waitcnt lgkmcnt(0)
	v_add_f32_e32 v40, v40, v41
	v_mov_b32_e32 v41, v40
	v_mov_b32_e32 v100, v40
	s_nop 1
	v_permlane16_swap_b32_e32 v41, v100
	v_add_f32_e32 v40, v41, v100
	v_mov_b32_e32 v41, v40
	v_mov_b32_e32 v100, v40
	s_nop 1
	v_permlane32_swap_b32_e32 v41, v100
	v_add_f32_e32 v57, v41, v100
	v_fma_mix_f32 v41, v57, s73, v36 op_sel:[0,0,1] op_sel_hi:[0,0,1]
	v_fma_mix_f32 v40, v57, s73, v36 op_sel_hi:[0,0,1]
	v_fma_mix_f32 v43, v57, s73, v37 op_sel:[0,0,1] op_sel_hi:[0,0,1]
	v_fma_mix_f32 v42, v57, s73, v37 op_sel_hi:[0,0,1]
	v_pk_mul_f32 v[36:37], v[42:43], v[42:43]
	v_pk_mul_f32 v[44:45], v[40:41], v[40:41]
	v_fma_mix_f32 v55, v57, s73, v35 op_sel:[0,0,1] op_sel_hi:[0,0,1]
	v_pk_mov_b32 v[46:47], v[44:45], v[36:37] op_sel:[1,0]
	v_mov_b32_e32 v45, v37
	v_pk_add_f32 v[36:37], v[46:47], v[44:45]
	v_fma_mix_f32 v45, v57, s73, v38 op_sel:[0,0,1] op_sel_hi:[0,0,1]
	v_fma_mix_f32 v44, v57, s73, v38 op_sel_hi:[0,0,1]
	v_fma_mix_f32 v47, v57, s73, v39 op_sel:[0,0,1] op_sel_hi:[0,0,1]
	v_fma_mix_f32 v46, v57, s73, v39 op_sel_hi:[0,0,1]
	v_pk_mul_f32 v[38:39], v[46:47], v[46:47]
	v_pk_mul_f32 v[48:49], v[44:45], v[44:45]
	v_pk_add_f32 v[36:37], v[36:37], v[36:37] op_sel_hi:[0,1]
	v_pk_mov_b32 v[50:51], v[48:49], v[38:39] op_sel:[1,0]
	v_mov_b32_e32 v49, v39
	v_pk_add_f32 v[38:39], v[50:51], v[48:49]
	v_fma_mix_f32 v48, v57, s73, v32 op_sel_hi:[0,0,1]
	v_fma_mix_f32 v49, v57, s73, v32 op_sel:[0,0,1] op_sel_hi:[0,0,1]
	v_mul_f32_e32 v32, v48, v48
	v_fma_mix_f32 v51, v57, s73, v33 op_sel:[0,0,1] op_sel_hi:[0,0,1]
	v_fma_mix_f32 v50, v57, s73, v33 op_sel_hi:[0,0,1]
	v_pk_fma_f32 v[32:33], v[48:49], v[48:49], v[32:33] op_sel_hi:[1,1,0]
	v_pk_add_f32 v[38:39], v[38:39], v[38:39] op_sel_hi:[0,1]
	v_mul_f32_e32 v32, v50, v50
	v_pk_fma_f32 v[52:53], v[50:51], v[50:51], v[32:33] op_sel_hi:[1,1,0]
	v_fma_mix_f32 v54, v57, s73, v35 op_sel_hi:[0,0,1]
	v_fma_mix_f32 v63, v57, s73, v34 op_sel:[0,0,1] op_sel_hi:[0,0,1]
	v_fma_mix_f32 v62, v57, s73, v34 op_sel_hi:[0,0,1]
	v_mul_f32_e32 v32, v62, v62
	v_mul_f32_e32 v52, v63, v63
	v_mul_f32_e32 v36, v54, v54
	v_mul_f32_e32 v38, v55, v55
	v_pk_add_f32 v[32:33], v[32:33], v[52:53]
	v_pk_add_f32 v[34:35], v[36:37], v[38:39]
	s_nop 0
	v_pk_add_f32 v[32:33], v[32:33], v[34:35]
	s_nop 0
	v_add_f32_e32 v32, v32, v33
	s_nop 1
	v_mov_b32_dpp v33, v32 quad_perm:[1,0,3,2] row_mask:0xf bank_mask:0xf
	s_waitcnt lgkmcnt(0)
	v_add_f32_e32 v32, v32, v33
	s_nop 1
	v_mov_b32_dpp v33, v32 quad_perm:[2,3,0,1] row_mask:0xf bank_mask:0xf
	s_waitcnt lgkmcnt(0)
	v_add_f32_e32 v32, v32, v33
	s_nop 1
	v_mov_b32_dpp v33, v32 row_ror:4 row_mask:0xf bank_mask:0xf
	s_waitcnt lgkmcnt(0)
	v_add_f32_e32 v32, v32, v33
	s_nop 1
	v_mov_b32_dpp v33, v32 row_ror:8 row_mask:0xf bank_mask:0xf
	s_waitcnt lgkmcnt(0)
	v_add_f32_e32 v32, v32, v33
	v_mov_b32_e32 v33, v32
	v_mov_b32_e32 v100, v32
	s_nop 1
	v_permlane16_swap_b32_e32 v33, v100
	v_add_f32_e32 v32, v33, v100
	v_mov_b32_e32 v33, v32
	v_mov_b32_e32 v100, v32
	s_nop 1
	v_permlane32_swap_b32_e32 v33, v100
	v_add_f32_e32 v32, v33, v100
	v_fmamk_f32 v32, v32, 0x3a800000, v213
	v_cmp_gt_f32_e32 vcc, s52, v32
	v_mul_f32_e32 v33, 0x4f800000, v32
	s_nop 0
	v_cndmask_b32_e32 v32, v32, v33, vcc
	v_sqrt_f32_e32 v33, v32
	s_nop 0
	v_add_u32_e32 v34, -1, v33
	v_fma_f32 v35, -v34, v33, v32
	v_cmp_ge_f32_e64 s[10:11], 0, v35
	v_add_u32_e32 v35, 1, v33
	s_nop 0
	v_cndmask_b32_e64 v34, v33, v34, s[10:11]
	v_fma_f32 v33, -v35, v33, v32
	v_cmp_lt_f32_e64 s[10:11], 0, v33
	s_nop 1
	v_cndmask_b32_e64 v33, v34, v35, s[10:11]
	v_mul_f32_e32 v34, 0x37800000, v33
	v_cndmask_b32_e32 v33, v33, v34, vcc
	v_cmp_class_f32_e32 vcc, v32, v214
	s_nop 1
	v_cndmask_b32_e32 v32, v33, v32, vcc
	v_div_scale_f32 v33, s[10:11], v32, v32, 1.0
	v_rcp_f32_e32 v34, v33
	s_movk_i32 s10, 0x7fff
	v_fma_f32 v35, -v33, v34, 1.0
	v_fmac_f32_e32 v34, v35, v34
	v_div_scale_f32 v35, vcc, 1.0, v32, 1.0
	v_mul_f32_e32 v36, v35, v34
	v_fma_f32 v37, -v33, v36, v35
	v_fmac_f32_e32 v36, v37, v34
	v_fma_f32 v33, -v33, v36, v35
	v_div_fmas_f32 v33, v33, v34, v36
	v_div_fixup_f32 v36, v33, v32, 1.0
	v_pk_mul_f32 v[32:33], v[40:41], v[36:37] op_sel_hi:[1,0]
	v_pk_mul_f32 v[34:35], v[42:43], v[36:37] op_sel_hi:[1,0]
	v_pk_fma_f32 v[40:41], v[4:5], v[32:33], v[12:13]
	v_pk_fma_f32 v[38:39], v[6:7], v[34:35], v[14:15]
	v_pk_mul_f32 v[32:33], v[44:45], v[36:37] op_sel_hi:[1,0]
	v_pk_mul_f32 v[34:35], v[46:47], v[36:37] op_sel_hi:[1,0]
	v_pk_fma_f32 v[32:33], v[0:1], v[32:33], v[8:9]
	v_pk_fma_f32 v[34:35], v[2:3], v[34:35], v[10:11]
	v_cmp_lt_i32_e32 vcc, s10, v56
	v_cvt_pk_f16_f32 v35, v34, v35
	v_cvt_pk_f16_f32 v34, v32, v33
	v_cvt_pk_f16_f32 v33, v38, v39
	v_cvt_pk_f16_f32 v32, v40, v41
	global_store_dwordx4 v[60:61], v[32:35], off
	s_or_b64 s[4:5], vcc, s[4:5]
	s_nop 0
	v_pk_mul_f32 v[32:33], v[48:49], v[36:37] op_sel_hi:[1,0]
	v_pk_mul_f32 v[34:35], v[50:51], v[36:37] op_sel_hi:[1,0]
	v_pk_fma_f32 v[40:41], v[20:21], v[32:33], v[28:29]
	v_pk_fma_f32 v[38:39], v[22:23], v[34:35], v[30:31]
	v_pk_mul_f32 v[32:33], v[62:63], v[36:37] op_sel_hi:[1,0]
	v_pk_mul_f32 v[34:35], v[54:55], v[36:37] op_sel_hi:[1,0]
	v_pk_fma_f32 v[32:33], v[16:17], v[32:33], v[24:25]
	v_pk_fma_f32 v[34:35], v[18:19], v[34:35], v[26:27]
	s_nop 0
	v_cvt_pk_f16_f32 v35, v34, v35
	v_cvt_pk_f16_f32 v34, v32, v33
	v_cvt_pk_f16_f32 v33, v38, v39
	v_cvt_pk_f16_f32 v32, v40, v41
	global_store_dwordx4 v[60:61], v[32:35], off offset:1024
	s_andn2_b64 exec, exec, s[4:5]
	s_cbranch_execnz .LBB0_1063
